# diff_attn phase: static s_setprio 1 for waves 0-3 (the older half), reset at phase exit; diff loop head pinned (stacked on v17)
# baseline (speedup 1.0000x reference)
; #define LAS __attribute__((address_space(3)))
; DI int mk_tid(int wv) { int w = wv; asm volatile("" : "+s"(w)); int l = __builtin_amdgcn_mbcnt_hi(~0u, __builtin_amdgcn_mbcnt_lo(~0u, 0u)); asm volatile("" : "+v"(l)); return w * 64 + l; }
; DI int opaque_bid() { int b = blockIdx.x; asm volatile("" : "+s"(b)); return b; }
; DI void diff_attn_phase(int wv, LAS unsigned char* lds, const bf16_t* qk, const bf16_t* vt, bf16_t* ob, const float* lq1, const float* lk1, const float* lq2, const float* lk2,
;                         const float* subg, int layer_idx) {
;     const int tid = mk_tid(wv), wid = __builtin_amdgcn_readfirstlane(tid >> 6), lane = tid & 63, rr = lane & 31, hh = lane >> 5; const int bid = opaque_bid();
;     const int map = wid >> 2, qsub = wid & 3;
;     int li_ = layer_idx; asm volatile("" : "+s"(li_)); const float lambda_init = (li_ == 0) ? 0.2f : 0.5560582041f;
;     const float d1 = wave_sum(lq1[lane] * lk1[lane]), d2 = wave_sum(lq2[lane] * lk2[lane]);
;     const float lam = expf(d1) - expf(d2) + lambda_init;
;     LAS float* xch = (LAS float*)lds;
;     const float c1 = 0.125f * LOG2E;
;     const int prr = (rr & 0x13) | ((rr & 4) << 1) | ((rr & 8) >> 1);
;     const int koff = prr * DA_KP + (map * 64 + hh * 8) * 2;
;     const int voff = DA_KB + rr * DA_VP + hh * 16;
;     const int krow0 = tid >> 4, kch = tid & 15, vrow0 = tid >> 3, vch = tid & 7;
;     const int kst_off = krow0 * DA_KP + kch * 16, vst_off = DA_KB + vrow0 * DA_VP + vch * 16;
.LBB0_416:
	s_andn2_b64 vcc, exec, s[0:1]
	s_cbranch_vccnz .LBB0_77
	v_readlane_b32 s0, v253, 54
	v_readlane_b32 s1, v253, 55
	s_load_dwordx8 s[8:15], s[0:1], 0x8
	s_mov_b32 s0, s68
	s_cmp_lt_u32 s68, 4
	s_cbranch_scc0 .Ldiff_prio_done
	s_setprio 1
.Ldiff_prio_done:
	v_mov_b32_e32 v3, v232
	s_mov_b32 s18, s55
	v_and_b32_e32 v2, 63, v3
	v_readlane_b32 s4, v253, 17
	v_lshlrev_b32_e32 v0, 2, v2
	s_waitcnt lgkmcnt(0)
	global_load_dword v4, v0, s[8:9]
	global_load_dword v5, v0, s[10:11]
	global_load_dword v6, v0, s[12:13]
	s_nop 0
	global_load_dword v0, v0, s[14:15]
	s_cmpk_gt_i32 s18, 0x7ff
	s_waitcnt vmcnt(0)
	v_mul_f32_e32 v7, v4, v5
	ds_bpermute_b32 v7, v233, v7
	v_mul_f32_e32 v8, v6, v0
	ds_bpermute_b32 v8, v233, v8
	s_waitcnt lgkmcnt(1)
	v_fmac_f32_e32 v7, v4, v5
	s_waitcnt lgkmcnt(0)
	v_fmac_f32_e32 v8, v6, v0
	ds_bpermute_b32 v0, v234, v7
	ds_bpermute_b32 v4, v234, v8
	s_waitcnt lgkmcnt(1)
	v_add_f32_e32 v0, v7, v0
	s_waitcnt lgkmcnt(0)
	v_add_f32_e32 v4, v8, v4
	ds_bpermute_b32 v5, v235, v0
	ds_bpermute_b32 v6, v235, v4
	s_waitcnt lgkmcnt(1)
	v_add_f32_e32 v0, v0, v5
	s_waitcnt lgkmcnt(0)
	v_add_f32_e32 v4, v4, v6
	ds_bpermute_b32 v5, v236, v0
	ds_bpermute_b32 v6, v236, v4
	s_waitcnt lgkmcnt(1)
	v_add_f32_e32 v0, v0, v5
	s_waitcnt lgkmcnt(0)
	v_add_f32_e32 v4, v4, v6
	ds_bpermute_b32 v5, v237, v0
	ds_bpermute_b32 v7, v237, v4
	s_waitcnt lgkmcnt(1)
	v_add_f32_e32 v6, v0, v5
	s_waitcnt lgkmcnt(0)
	v_add_f32_e32 v0, v4, v7
	ds_bpermute_b32 v7, v238, v6
	ds_bpermute_b32 v5, v238, v0
	v_lshl_add_u32 v4, s0, 6, v3
	s_nop 0
	v_readfirstlane_b32 s10, v4
	s_cbranch_scc1 .LBB0_440
	s_waitcnt lgkmcnt(1)
	v_add_f32_e32 v6, v6, v7
	v_mul_f32_e32 v7, 0x3fb8aa3b, v6
	s_mov_b32 s3, 0x3fb8aa3b
	v_fma_f32 v9, v6, s3, -v7
	v_rndne_f32_e32 v10, v7
	v_fmac_f32_e32 v9, 0x32a5705f, v6
	v_sub_f32_e32 v7, v7, v10
	v_add_f32_e32 v7, v7, v9
	v_exp_f32_e32 v7, v7
	v_cvt_i32_f32_e32 v9, v10
	s_ashr_i32 s2, s10, 8
	s_cmp_eq_u32 s4, 0
	s_waitcnt lgkmcnt(0)
	v_add_f32_e32 v0, v0, v5
	s_cselect_b64 vcc, -1, 0
	v_mov_b32_e32 v10, 0x3f0e59d5
	v_mov_b32_e32 v11, 0x3e4ccccd
	v_ldexp_f32 v5, v7, v9
	v_mul_f32_e32 v7, 0x3fb8aa3b, v0
	v_cndmask_b32_e32 v10, v10, v11, vcc
	v_fma_f32 v9, v0, s3, -v7
	v_rndne_f32_e32 v11, v7
	v_fmac_f32_e32 v9, 0x32a5705f, v0
	v_sub_f32_e32 v7, v7, v11
	v_add_f32_e32 v7, v7, v9
	v_exp_f32_e32 v7, v7
	v_cvt_i32_f32_e32 v9, v11
	s_mov_b32 s3, 0xc2ce8ed0
	v_cmp_ngt_f32_e32 vcc, s3, v6
	s_mov_b32 s4, 0x42b17218
	v_ashrrev_i32_e32 v161, 3, v4
	v_cndmask_b32_e32 v5, 0, v5, vcc
	v_cmp_nlt_f32_e32 vcc, s4, v6
	v_ldexp_f32 v6, v7, v9
	v_readlane_b32 s8, v253, 0
	v_cndmask_b32_e32 v5, v246, v5, vcc
	v_cmp_ngt_f32_e32 vcc, s3, v0
	s_movk_i32 s3, 0x110
	v_readlane_b32 s9, v253, 1
	v_cndmask_b32_e32 v6, 0, v6, vcc
	v_cmp_nlt_f32_e32 vcc, s4, v0
	s_lshl_b32 s4, s2, 6
	s_ashr_i32 s5, s4, 31
	v_cndmask_b32_e32 v0, v246, v6, vcc
	v_sub_f32_e32 v0, v5, v0
	v_lshlrev_b32_e32 v5, 1, v3
	v_lshrrev_b32_e32 v6, 1, v3
	v_add_f32_e32 v149, v10, v0
	v_and_b32_e32 v0, 19, v3
	v_and_b32_e32 v5, 8, v5
	v_and_b32_e32 v6, 4, v6
	v_or3_b32 v0, v0, v5, v6
	v_ashrrev_i32_e32 v6, 4, v4
	v_mul_lo_u32 v4, v6, s3
	s_ashr_i32 s3, s10, 6
	s_and_b32 s11, s3, 3
	s_lshl_b32 s3, s3, 12
	s_add_i32 s3, s3, 0
	s_lshl_b32 s19, s11, 5
	s_add_i32 s3, s3, 0x11800
	s_cmp_eq_u32 s2, 1
	s_load_dword s2, s[8:9], 0x10
	v_readlane_b32 s0, v253, 54
	v_readlane_b32 s1, v253, 55
	s_cselect_b64 s[6:7], -1, 0
	s_cmpk_lt_u32 s10, 0x100
	s_load_dwordx2 s[0:1], s[0:1], 0x28
	s_cselect_b64 s[8:9], -1, 0
	s_waitcnt lgkmcnt(0)
	s_lshr_b32 s2, s2, 16
	v_lshrrev_b32_e32 v8, 5, v2
	s_cmp_lg_u32 s2, 0
	v_lshlrev_b32_e32 v146, 3, v8
	s_cselect_b64 s[12:13], -1, 0
	v_mul_u32_u24_e32 v0, 0x110, v0
	v_or_b32_e32 v5, s4, v146
	s_cmp_lg_u64 s[12:13], 0
	v_and_b32_e32 v147, 31, v3
	v_lshl_add_u32 v153, v5, 1, v0
	v_lshlrev_b32_e32 v0, 4, v8
	s_movk_i32 s14, 0x90
	s_addc_u32 s20, s46, 0
	s_lshl_b32 s2, s10, 8
	v_and_b32_e32 v5, 15, v3
	v_mad_u32_u24 v211, v147, s14, v0
	s_and_b32 s10, s2, 0xc000
	s_or_b32 s21, s2, 0x3f00
	v_lshl_add_u64 v[154:155], s[0:1], 0, v[0:1]
	v_sub_u32_e32 v0, v146, v147
	v_and_b32_e32 v3, 7, v3
	v_lshl_add_u32 v167, v5, 4, v4
	v_mul_lo_u32 v4, v161, s14
	v_lshlrev_b32_e32 v9, 4, v2
	v_ashrrev_i32_e32 v7, 31, v6
	v_lshl_add_u32 v209, v2, 2, 0
	v_lshlrev_b32_e32 v2, 2, v8
	v_add_u32_e32 v212, 0, v211
	s_cmp_lt_u32 s11, 2
	v_subrev_u32_e32 v0, s19, v0
	v_lshlrev_b32_e32 v148, 3, v5
	v_lshlrev_b64 v[150:151], 11, v[6:7]
	v_lshlrev_b32_e32 v152, 3, v3
	v_lshl_add_u32 v208, v3, 4, v4
	v_sub_f32_e32 v210, 1.0, v10
	v_add_u32_e32 v213, 0xd000, v212
	v_lshl_add_u32 v214, s11, 14, v209
	v_add_u32_e32 v215, s10, v209
	s_cselect_b64 s[10:11], -1, 0
	v_add_u32_e32 v216, 0xfffff200, v0
	s_mov_b64 s[12:13], 0
	v_lshlrev_b32_e32 v156, 1, v146
	v_lshlrev_b32_e32 v158, 1, v2
	v_add_u32_e32 v217, s3, v9
	s_branch .LBB0_420

; #define LAS __attribute__((address_space(3)))
; DI int mk_tid(int wv) { int w = wv; asm volatile("" : "+s"(w)); int l = __builtin_amdgcn_mbcnt_hi(~0u, __builtin_amdgcn_mbcnt_lo(~0u, 0u)); asm volatile("" : "+v"(l)); return w * 64 + l; }
; DI size_t opq_off(size_t o) { asm volatile("" : "+s"(o)); return o; }
; DI unsigned xcc_id() { return (unsigned)__builtin_amdgcn_s_getreg((3 << 11) | 20) & 0xFu; }
; DI void grid_barrier(int wv, unsigned* bar_, unsigned k, LAS unsigned* stash) {
;     unsigned* bar = bar_ + opq_off(0);
;     asm volatile("s_waitcnt vmcnt(0) lgkmcnt(0)" ::: "memory");
;     __syncthreads();
;     if (mk_tid(wv) == 0) {
;         const unsigned xcc = xcc_id(), nx = stash[0], nxcc = stash[1];
;         const unsigned old = __hip_atomic_fetch_add(bar + 64 * (17 + xcc), 1u, __ATOMIC_RELAXED, __HIP_MEMORY_SCOPE_AGENT);
.LBB0_440:
	s_setprio 0
	v_readlane_b32 s0, v254, 28
	s_add_i32 s22, s0, 2
	s_cmp_ge_i32 s22, s51
	s_cbranch_scc1 .LBB0_77
	s_cmp_lg_u32 s75, s50
	s_mov_b64 s[0:1], -1
	s_cbranch_scc0 .LBB0_455
	s_mov_b64 s[4:5], 0x1eb00000
	s_mov_b64 s[6:7], 0
	s_mov_b32 s0, s68
	s_waitcnt vmcnt(0) lgkmcnt(0)
	s_waitcnt lgkmcnt(0)
	s_barrier
	s_lshl_b32 s0, s0, 6
	v_mov_b32_e32 v2, v232
	s_sub_i32 s0, 0, s0
	v_add_u32_e32 v0, 1, v252
	s_nop 0
	v_cmp_eq_u32_e32 vcc, s0, v2
	s_and_saveexec_b64 s[0:1], vcc
	s_cbranch_execz .LBB0_454
	s_add_u32 s2, s48, s4
	s_addc_u32 s3, s49, s5
	s_lshl_b64 s[4:5], s[6:7], 2
	s_add_u32 s4, s2, s4
	v_readlane_b32 s2, v253, 3
	s_getreg_b32 s10, hwreg(HW_REG_XCC_ID, 0, 4)
	s_mov_b64 s[6:7], exec
	v_mov_b32_e32 v2, s2
	ds_read_b64 v[2:3], v2
	v_mbcnt_lo_u32_b32 v4, s6, 0
	v_mbcnt_hi_u32_b32 v4, s7, v4
	s_addc_u32 s5, s3, s5
	v_cmp_eq_u32_e32 vcc, 0, v4
	s_and_saveexec_b64 s[8:9], vcc
	s_cbranch_execz .LBB0_445
	s_lshl_b32 s2, s10, 8
	s_and_b32 s2, s2, 0xf00
	s_add_u32 s10, s4, s2
	s_addc_u32 s11, s5, 0
	s_bcnt1_i32_b64 s2, s[6:7]
	v_mov_b32_e32 v5, s2
	global_atomic_add v5, v239, v5, s[10:11] offset:256 sc0
